# kfix: 16-lane sum-of-squares reductions via DPP (quad_perm + row_ror) instead of ds_bpermute round trips
# baseline (speedup 1.0000x reference)
.LBB0_322:
	v_lshl_add_u64 v[16:17], s[8:9], 0, v[14:15]
	v_add_co_u32_e32 v16, vcc, 0x28f00000, v16
	s_mov_b32 s2, 0x1100000
	s_nop 0
	v_addc_co_u32_e32 v17, vcc, 0, v17, vcc
	global_load_dwordx4 v[32:35], v[16:17], off
	global_load_dwordx4 v[184:187], v[16:17], off offset:1024
	global_load_dwordx4 v[188:191], v[16:17], off offset:2048
	global_load_dwordx4 v[192:195], v[16:17], off offset:3072
	v_lshl_add_u64 v[240:241], s[8:9], 0, v[12:13]
	global_load_dword v208, v[240:241], off
	v_lshl_add_u64 v[240:241], s[8:9], 0, v[8:9]
	v_add_co_u32_e32 v242, vcc, 0x1100000, v240
	s_nop 1
	v_addc_co_u32_e32 v243, vcc, 0, v241, vcc
	global_load_dword v209, v[242:243], off
	v_add_co_u32_e32 v242, vcc, 0x1300000, v240
	s_nop 1
	v_addc_co_u32_e32 v243, vcc, 0, v241, vcc
	global_load_dword v210, v[242:243], off
	v_add_u32_e32 v2, s52, v2
	v_lshl_add_u64 v[14:15], v[14:15], 0, s[30:31]
	s_waitcnt vmcnt(0) lgkmcnt(0)
	v_and_b32_e32 v23, 0xffff0000, v33
	v_and_b32_e32 v22, 0xffff0000, v32
	v_lshlrev_b32_e32 v25, 16, v33
	v_lshlrev_b32_e32 v24, 16, v32
	v_pk_mul_f32 v[18:19], v[22:23], v[22:23]
	v_lshlrev_b32_e32 v21, 16, v35
	v_pk_fma_f32 v[32:33], v[24:25], v[24:25], v[18:19]
	v_and_b32_e32 v19, 0xffff0000, v35
	v_add_f32_e32 v0, v32, v33
	v_mov_b32_e32 v32, v176
	v_mov_b32_e32 v33, v177
	v_and_b32_e32 v18, 0xffff0000, v34
	v_lshlrev_b32_e32 v20, 16, v34
	v_pk_mul_f32 v[34:35], v[18:19], v[18:19]
	s_nop 0
	v_pk_fma_f32 v[34:35], v[20:21], v[20:21], v[34:35]
	s_nop 0
	v_add_f32_e32 v0, v34, v0
	v_add_f32_e32 v0, v35, v0
	s_nop 1
	v_add_f32_dpp v0, v0, v0 quad_perm:[1,0,3,2] row_mask:0xf bank_mask:0xf
	s_nop 1
	v_add_f32_dpp v0, v0, v0 quad_perm:[2,3,0,1] row_mask:0xf bank_mask:0xf
	s_nop 1
	v_add_f32_dpp v0, v0, v0 row_ror:4 row_mask:0xf bank_mask:0xf
	s_nop 1
	v_add_f32_dpp v0, v0, v0 row_ror:8 row_mask:0xf bank_mask:0xf
	v_fmamk_f32 v0, v0, 0x3c000000, v207
	v_cmp_gt_f32_e32 vcc, s87, v0
	v_mul_f32_e32 v3, 0x4b800000, v0
	s_nop 0
	v_cndmask_b32_e32 v0, v0, v3, vcc
	v_rsq_f32_e32 v0, v0
	s_nop 0
	v_mul_f32_e32 v3, 0x45800000, v0
	v_cndmask_b32_e32 v0, v0, v3, vcc
	v_mul_f32_e32 v3, v0, v24
	v_mul_f32_e32 v22, v0, v22
	v_mul_f32_e32 v23, v0, v23
	v_mul_f32_e32 v18, v0, v18

	v_mul_f32_e32 v3, v32, v3
	v_mul_f32_e32 v22, v33, v22
	v_cvt_pk_bf16_f32 v22, v3, v22
	v_mul_f32_e32 v3, v0, v25
	v_mov_b32_e32 v24, v178
	v_mov_b32_e32 v25, v179
	v_mul_f32_e32 v23, v25, v23
	v_mul_f32_e32 v3, v24, v3
	v_cvt_pk_bf16_f32 v23, v3, v23
	v_mov_b32_e32 v24, v180
	v_mov_b32_e32 v25, v181
	v_mul_f32_e32 v3, v0, v20
	v_mul_f32_e32 v3, v24, v3
	v_mul_f32_e32 v18, v25, v18
	v_cvt_pk_bf16_f32 v24, v3, v18
	v_mul_f32_e32 v3, v0, v21
	v_mov_b32_e32 v20, v182
	v_mov_b32_e32 v21, v183
	v_mul_f32_e32 v0, v0, v19
	v_mul_f32_e32 v3, v20, v3
	v_mul_f32_e32 v0, v21, v0
	v_cvt_pk_bf16_f32 v25, v3, v0
	v_mov_b32_e32 v32, v184
	v_mov_b32_e32 v33, v185
	v_mov_b32_e32 v34, v186
	v_mov_b32_e32 v35, v187
	v_lshlrev_b32_e32 v21, 16, v35
	global_store_dwordx4 v[16:17], v[22:25], off
	v_lshlrev_b32_e32 v20, 16, v34
	s_nop 0
	v_and_b32_e32 v23, 0xffff0000, v33
	v_and_b32_e32 v22, 0xffff0000, v32
	v_lshlrev_b32_e32 v25, 16, v33
	v_lshlrev_b32_e32 v24, 16, v32
	v_pk_mul_f32 v[18:19], v[22:23], v[22:23]
	s_nop 0
	v_pk_fma_f32 v[32:33], v[24:25], v[24:25], v[18:19]
	v_and_b32_e32 v19, 0xffff0000, v35
	v_add_f32_e32 v0, v32, v33
	v_mov_b32_e32 v32, v176
	v_mov_b32_e32 v33, v177
	v_and_b32_e32 v18, 0xffff0000, v34
	v_pk_mul_f32 v[34:35], v[18:19], v[18:19]
	s_nop 0
	v_pk_fma_f32 v[34:35], v[20:21], v[20:21], v[34:35]
	s_nop 0
	v_add_f32_e32 v0, v34, v0
	v_add_f32_e32 v0, v35, v0
	s_nop 1
	v_add_f32_dpp v0, v0, v0 quad_perm:[1,0,3,2] row_mask:0xf bank_mask:0xf
	s_nop 1
	v_add_f32_dpp v0, v0, v0 quad_perm:[2,3,0,1] row_mask:0xf bank_mask:0xf
	s_nop 1
	v_add_f32_dpp v0, v0, v0 row_ror:4 row_mask:0xf bank_mask:0xf
	s_nop 1
	v_add_f32_dpp v0, v0, v0 row_ror:8 row_mask:0xf bank_mask:0xf
	v_fmamk_f32 v0, v0, 0x3c000000, v207
	v_cmp_gt_f32_e32 vcc, s87, v0
	v_mul_f32_e32 v3, 0x4b800000, v0
	s_nop 0
	v_cndmask_b32_e32 v0, v0, v3, vcc
	v_rsq_f32_e32 v0, v0
	s_nop 0
	v_mul_f32_e32 v3, 0x45800000, v0
	v_cndmask_b32_e32 v0, v0, v3, vcc
	v_mul_f32_e32 v3, v0, v24
	v_mul_f32_e32 v22, v0, v22
	v_mul_f32_e32 v23, v0, v23
	v_mul_f32_e32 v18, v0, v18

	v_mul_f32_e32 v3, v32, v3
	v_mul_f32_e32 v22, v33, v22
	v_cvt_pk_bf16_f32 v22, v3, v22
	v_mul_f32_e32 v3, v0, v25
	v_mov_b32_e32 v24, v178
	v_mov_b32_e32 v25, v179
	v_mul_f32_e32 v23, v25, v23
	v_mul_f32_e32 v3, v24, v3
	v_cvt_pk_bf16_f32 v23, v3, v23
	v_mov_b32_e32 v24, v180
	v_mov_b32_e32 v25, v181
	v_mul_f32_e32 v3, v0, v20
	v_mul_f32_e32 v3, v24, v3
	v_mul_f32_e32 v18, v25, v18
	v_cvt_pk_bf16_f32 v24, v3, v18
	v_mul_f32_e32 v3, v0, v21
	v_mov_b32_e32 v20, v182
	v_mov_b32_e32 v21, v183
	v_mul_f32_e32 v0, v0, v19
	v_mul_f32_e32 v3, v20, v3
	v_mul_f32_e32 v0, v21, v0
	v_cvt_pk_bf16_f32 v25, v3, v0
	v_mov_b32_e32 v32, v188
	v_mov_b32_e32 v33, v189
	v_mov_b32_e32 v34, v190
	v_mov_b32_e32 v35, v191
	v_lshlrev_b32_e32 v21, 16, v35
	global_store_dwordx4 v[16:17], v[22:25], off offset:1024
	v_lshlrev_b32_e32 v20, 16, v34
	s_nop 0
	v_and_b32_e32 v23, 0xffff0000, v33
	v_and_b32_e32 v22, 0xffff0000, v32
	v_lshlrev_b32_e32 v25, 16, v33
	v_lshlrev_b32_e32 v24, 16, v32
	v_pk_mul_f32 v[18:19], v[22:23], v[22:23]
	s_nop 0
	v_pk_fma_f32 v[32:33], v[24:25], v[24:25], v[18:19]
	v_and_b32_e32 v19, 0xffff0000, v35
	v_add_f32_e32 v0, v32, v33
	v_mov_b32_e32 v32, v176
	v_mov_b32_e32 v33, v177
	v_and_b32_e32 v18, 0xffff0000, v34
	v_pk_mul_f32 v[34:35], v[18:19], v[18:19]
	s_nop 0
	v_pk_fma_f32 v[34:35], v[20:21], v[20:21], v[34:35]
	s_nop 0
	v_add_f32_e32 v0, v34, v0
	v_add_f32_e32 v0, v35, v0
	s_nop 1
	v_add_f32_dpp v0, v0, v0 quad_perm:[1,0,3,2] row_mask:0xf bank_mask:0xf
	s_nop 1
	v_add_f32_dpp v0, v0, v0 quad_perm:[2,3,0,1] row_mask:0xf bank_mask:0xf
	s_nop 1
	v_add_f32_dpp v0, v0, v0 row_ror:4 row_mask:0xf bank_mask:0xf
	s_nop 1
	v_add_f32_dpp v0, v0, v0 row_ror:8 row_mask:0xf bank_mask:0xf
	v_fmamk_f32 v0, v0, 0x3c000000, v207
	v_cmp_gt_f32_e32 vcc, s87, v0
	v_mul_f32_e32 v3, 0x4b800000, v0
	s_nop 0
	v_cndmask_b32_e32 v0, v0, v3, vcc
	v_rsq_f32_e32 v0, v0
	s_nop 0
	v_mul_f32_e32 v3, 0x45800000, v0
	v_cndmask_b32_e32 v0, v0, v3, vcc
	v_mul_f32_e32 v3, v0, v24
	v_mul_f32_e32 v22, v0, v22
	v_mul_f32_e32 v23, v0, v23
	v_mul_f32_e32 v18, v0, v18

	v_mul_f32_e32 v3, v32, v3
	v_mul_f32_e32 v22, v33, v22
	v_cvt_pk_bf16_f32 v22, v3, v22
	v_mul_f32_e32 v3, v0, v25
	v_mov_b32_e32 v24, v178
	v_mov_b32_e32 v25, v179
	v_mul_f32_e32 v23, v25, v23
	v_mul_f32_e32 v3, v24, v3
	v_cvt_pk_bf16_f32 v23, v3, v23
	v_mov_b32_e32 v24, v180
	v_mov_b32_e32 v25, v181
	v_mul_f32_e32 v3, v0, v20
	v_mul_f32_e32 v3, v24, v3
	v_mul_f32_e32 v18, v25, v18
	v_cvt_pk_bf16_f32 v24, v3, v18
	v_mul_f32_e32 v3, v0, v21
	v_mov_b32_e32 v20, v182
	v_mov_b32_e32 v21, v183
	v_mul_f32_e32 v0, v0, v19
	v_mul_f32_e32 v3, v20, v3
	v_mul_f32_e32 v0, v21, v0
	v_cvt_pk_bf16_f32 v25, v3, v0
	v_mov_b32_e32 v32, v192
	v_mov_b32_e32 v33, v193
	v_mov_b32_e32 v34, v194
	v_mov_b32_e32 v35, v195
	v_lshlrev_b32_e32 v21, 16, v35
	global_store_dwordx4 v[16:17], v[22:25], off offset:2048
	v_lshlrev_b32_e32 v20, 16, v34
	s_nop 0
	v_and_b32_e32 v23, 0xffff0000, v33
	v_and_b32_e32 v22, 0xffff0000, v32
	v_lshlrev_b32_e32 v25, 16, v33
	v_lshlrev_b32_e32 v24, 16, v32
	v_pk_mul_f32 v[18:19], v[22:23], v[22:23]
	s_nop 0
	v_pk_fma_f32 v[32:33], v[24:25], v[24:25], v[18:19]
	v_and_b32_e32 v19, 0xffff0000, v35
	v_add_f32_e32 v0, v32, v33
	v_mov_b32_e32 v32, v176
	v_mov_b32_e32 v33, v177
	v_and_b32_e32 v18, 0xffff0000, v34
	v_pk_mul_f32 v[34:35], v[18:19], v[18:19]
	s_nop 0
	v_pk_fma_f32 v[34:35], v[20:21], v[20:21], v[34:35]
	s_nop 0
	v_add_f32_e32 v0, v34, v0
	v_add_f32_e32 v0, v35, v0
	s_nop 1
	v_add_f32_dpp v0, v0, v0 quad_perm:[1,0,3,2] row_mask:0xf bank_mask:0xf
	s_nop 1
	v_add_f32_dpp v0, v0, v0 quad_perm:[2,3,0,1] row_mask:0xf bank_mask:0xf
	s_nop 1
	v_add_f32_dpp v0, v0, v0 row_ror:4 row_mask:0xf bank_mask:0xf
	s_nop 1
	v_add_f32_dpp v0, v0, v0 row_ror:8 row_mask:0xf bank_mask:0xf
	v_fmamk_f32 v0, v0, 0x3c000000, v207
	v_cmp_gt_f32_e32 vcc, s87, v0
	v_mul_f32_e32 v3, 0x4b800000, v0
	s_nop 0
	v_cndmask_b32_e32 v0, v0, v3, vcc
	v_rsq_f32_e32 v0, v0
	s_nop 0
	v_mul_f32_e32 v3, 0x45800000, v0
	v_cndmask_b32_e32 v0, v0, v3, vcc
	v_mul_f32_e32 v3, v0, v24
	v_mul_f32_e32 v22, v0, v22
	v_mul_f32_e32 v23, v0, v23
	v_mul_f32_e32 v18, v0, v18

	v_mul_f32_e32 v3, v32, v3
	v_mul_f32_e32 v22, v33, v22
	v_cvt_pk_bf16_f32 v22, v3, v22
	v_mul_f32_e32 v3, v0, v25
	v_mov_b32_e32 v24, v178
	v_mov_b32_e32 v25, v179
	v_mul_f32_e32 v23, v25, v23
	v_mul_f32_e32 v3, v24, v3
	v_cvt_pk_bf16_f32 v23, v3, v23
	v_mov_b32_e32 v24, v180
	v_mov_b32_e32 v25, v181
	v_mul_f32_e32 v3, v0, v20
	v_mul_f32_e32 v3, v24, v3
	v_mul_f32_e32 v18, v25, v18
	v_cvt_pk_bf16_f32 v24, v3, v18
	v_mul_f32_e32 v3, v0, v21
	v_mov_b32_e32 v20, v182
	v_mov_b32_e32 v21, v183
	v_mul_f32_e32 v0, v0, v19
	v_mul_f32_e32 v3, v20, v3
	v_mul_f32_e32 v0, v21, v0
	v_cvt_pk_bf16_f32 v25, v3, v0
	global_store_dwordx4 v[16:17], v[22:25], off offset:3072
	v_lshl_add_u64 v[16:17], s[8:9], 0, v[12:13]
	v_mov_b32_e32 v0, v208
	v_lshl_add_u64 v[12:13], v[12:13], 0, s[18:19]
	s_nop 0
	v_mul_f32_e32 v3, v0, v0
	ds_bpermute_b32 v3, v26, v3
	s_waitcnt lgkmcnt(0)
	v_fmac_f32_e32 v3, v0, v0
	ds_bpermute_b32 v16, v27, v3
	s_waitcnt lgkmcnt(0)
	v_add_f32_e32 v3, v3, v16
	ds_bpermute_b32 v16, v28, v3
	s_waitcnt lgkmcnt(0)
	v_add_f32_e32 v3, v3, v16
	ds_bpermute_b32 v16, v29, v3
	s_waitcnt lgkmcnt(0)
	v_add_f32_e32 v3, v3, v16
	ds_bpermute_b32 v16, v30, v3
	s_waitcnt lgkmcnt(0)
	v_add_f32_e32 v3, v3, v16
	ds_bpermute_b32 v16, v31, v3
	s_waitcnt lgkmcnt(0)
	v_add_f32_e32 v3, v3, v16
	v_fmamk_f32 v3, v3, 0x3c800000, v207
	v_cmp_gt_f32_e32 vcc, s87, v3
	v_mul_f32_e32 v16, 0x4b800000, v3
	s_nop 0
	v_cndmask_b32_e32 v3, v3, v16, vcc
	v_rsq_f32_e32 v3, v3
	s_nop 0
	v_mul_f32_e32 v16, 0x45800000, v3
	v_cndmask_b32_e32 v3, v3, v16, vcc
	v_mul_f32_e32 v0, v0, v3
	v_mov_b32_e32 v3, v211
	v_lshl_add_u64 v[16:17], s[8:9], 0, v[8:9]
	v_add_co_u32_e32 v18, vcc, s2, v16
	s_mov_b32 s2, 0x1300000
	s_nop 0
	v_addc_co_u32_e32 v19, vcc, 0, v17, vcc
	v_add_co_u32_e32 v16, vcc, s2, v16
	v_mov_b32_e32 v18, v209
	s_nop 0
	v_addc_co_u32_e32 v17, vcc, 0, v17, vcc
	v_mov_b32_e32 v16, v210
	s_movk_i32 s2, 0x3fff
	v_cmp_lt_i32_e32 vcc, s2, v2
	v_lshl_add_u64 v[8:9], v[8:9], 0, s[14:15]
	s_or_b64 s[4:5], vcc, s[4:5]
	s_waitcnt lgkmcnt(0)
	v_mul_f32_e32 v0, v3, v0
	ds_bpermute_b32 v3, v31, v0
	s_waitcnt lgkmcnt(0)
	v_mul_f32_e32 v3, v16, v3
	v_cndmask_b32_e64 v3, v3, -v3, s[36:37]
	v_fmac_f32_e32 v3, v18, v0
	v_bfe_u32 v0, v3, 16, 1
	v_add3_u32 v0, v3, v0, s10
	v_lshl_add_u64 v[16:17], s[8:9], 0, v[10:11]
	v_lshl_add_u64 v[10:11], v[10:11], 0, s[14:15]
	global_store_short_d16_hi v[16:17], v0, off
	s_andn2_b64 exec, exec, s[4:5]
	s_cbranch_execnz .LBB0_322
